# weight conversion: gain multiply of the prefetched tile deferred to the consumer (next iteration head), loads stay in flight across the LDS transposition
# speedup vs baseline: 1.0171x; 1.0075x over previous
.LBB0_268:
	s_waitcnt vmcnt(10)
	v_ashrrev_i32_e32 v24, 5, v22
	v_add_u32_e32 v8, s10, v24
	v_mad_i64_i32 v[6:7], s[4:5], s14, v8, 0
	v_and_b32_e32 v2, 60, v23
	v_lshl_add_u64 v[6:7], v[6:7], 2, s[16:17]
	v_ashrrev_i32_e32 v5, 31, v4
	v_lshl_add_u64 v[4:5], v[4:5], 2, v[6:7]
	v_lshlrev_b32_e32 v2, 2, v2
	v_lshl_add_u64 v[4:5], v[4:5], 0, v[2:3]
	s_mov_b32 s86, 0
	global_load_dwordx4 v[4:7], v[4:5], off
	s_cmp_lg_u64 s[12:13], 0
	s_cselect_b64 s[18:19], -1, 0
	s_cmp_eq_u64 s[12:13], 0
	s_cbranch_scc1 .LBB0_270
	v_ashrrev_i32_e32 v9, 31, v8
	v_lshl_add_u64 v[8:9], v[8:9], 2, s[12:13]
	global_load_dword v242, v[8:9], off

.LBB0_280:
	v_add_u32_e32 v17, 0x600, v22
	v_ashrrev_i32_e32 v27, 5, v17
	v_add_u32_e32 v20, s10, v27
	v_mad_i64_i32 v[18:19], s[0:1], s14, v20, 0
	v_lshl_add_u64 v[18:19], v[18:19], 2, s[16:17]
	v_ashrrev_i32_e32 v17, 31, v16
	v_lshl_add_u64 v[16:17], v[16:17], 2, v[18:19]
	v_lshl_add_u64 v[16:17], v[16:17], 0, v[2:3]
	global_load_dwordx4 v[16:19], v[16:17], off
	s_and_b64 vcc, exec, s[4:5]
	s_cbranch_vccnz .LBB0_282
	v_ashrrev_i32_e32 v21, 31, v20
	v_lshl_add_u64 v[20:21], v[20:21], 2, s[12:13]
	global_load_dword v248, v[20:21], off
	s_mov_b32 s86, 1

.LBB0_284:
	s_cmp_eq_u32 s86, 0
	s_cbranch_scc1 .Lcg_nog_3
	s_waitcnt vmcnt(0)
	v_pk_mul_f32 v[6:7], v[6:7], v[242:243] op_sel_hi:[1,0]
	v_pk_mul_f32 v[4:5], v[4:5], v[242:243] op_sel_hi:[1,0]
	v_pk_mul_f32 v[10:11], v[10:11], v[244:245] op_sel_hi:[1,0]
	v_pk_mul_f32 v[8:9], v[8:9], v[244:245] op_sel_hi:[1,0]
	v_pk_mul_f32 v[14:15], v[14:15], v[246:247] op_sel_hi:[1,0]
	v_pk_mul_f32 v[12:13], v[12:13], v[246:247] op_sel_hi:[1,0]
	v_pk_mul_f32 v[18:19], v[18:19], v[248:249] op_sel_hi:[1,0]
	v_pk_mul_f32 v[16:17], v[16:17], v[248:249] op_sel_hi:[1,0]

.LBB0_294:
	v_add_u32_e32 v8, s42, v24
	v_ashrrev_i32_e32 v9, 31, v8
	v_mul_lo_u32 v5, s26, v9
	v_mul_lo_u32 v10, s27, v8
	v_mad_u64_u32 v[6:7], s[4:5], s26, v8, 0
	v_add3_u32 v7, v7, v5, v10
	v_lshl_add_u64 v[6:7], v[6:7], 2, s[28:29]
	v_ashrrev_i32_e32 v5, 31, v4
	v_lshl_add_u64 v[4:5], v[4:5], 2, v[6:7]
	v_lshl_add_u64 v[4:5], v[4:5], 0, v[2:3]
	s_mov_b32 s86, 0
	global_load_dwordx4 v[4:7], v[4:5], off
	s_cmp_lg_u64 s[24:25], 0
	s_cselect_b64 s[30:31], -1, 0
	s_cmp_eq_u64 s[24:25], 0
	s_cbranch_scc1 .LBB0_296
	v_lshl_add_u64 v[8:9], v[8:9], 2, s[24:25]
	global_load_dword v242, v[8:9], off

.LBB0_306:
	v_add_u32_e32 v22, s42, v27
	v_ashrrev_i32_e32 v23, 31, v22
	v_mul_lo_u32 v17, s26, v23
	v_mul_lo_u32 v21, s27, v22
	v_mad_u64_u32 v[18:19], s[0:1], s26, v22, 0
	v_add3_u32 v19, v19, v17, v21
	v_lshl_add_u64 v[18:19], v[18:19], 2, s[28:29]
	v_ashrrev_i32_e32 v17, 31, v16
	v_lshl_add_u64 v[16:17], v[16:17], 2, v[18:19]
	v_lshl_add_u64 v[16:17], v[16:17], 0, v[2:3]
	global_load_dwordx4 v[16:19], v[16:17], off
	s_and_b64 vcc, exec, s[4:5]
	s_cbranch_vccnz .LBB0_283
	v_lshl_add_u64 v[22:23], v[22:23], 2, s[24:25]
	global_load_dword v248, v[22:23], off
	s_mov_b32 s86, 1
	s_branch .LBB0_283

.LBB0_423:
	v_ashrrev_i32_e32 v23, 5, v28
	v_add_u32_e32 v8, s8, v23
	v_ashrrev_i32_e32 v9, 31, v8
	v_mul_lo_u32 v5, s14, v9
	v_mul_lo_u32 v10, s15, v8
	v_mad_u64_u32 v[6:7], s[4:5], s14, v8, 0
	v_add3_u32 v7, v7, v5, v10
	v_and_b32_e32 v2, 60, v27
	v_lshl_add_u64 v[6:7], v[6:7], 2, s[12:13]
	v_ashrrev_i32_e32 v5, 31, v4
	v_lshl_add_u64 v[4:5], v[4:5], 2, v[6:7]
	v_lshlrev_b32_e32 v2, 2, v2
	v_lshl_add_u64 v[4:5], v[4:5], 0, v[2:3]
	s_mov_b32 s86, 0
	global_load_dwordx4 v[4:7], v[4:5], off
	s_cmp_lg_u64 s[10:11], 0
	s_cselect_b64 s[16:17], -1, 0
	s_cmp_eq_u64 s[10:11], 0
	s_cbranch_scc1 .LBB0_425
	v_lshl_add_u64 v[8:9], v[8:9], 2, s[10:11]
	global_load_dword v242, v[8:9], off

.LBB0_435:
	v_add_u32_e32 v1, 0x600, v28
	v_ashrrev_i32_e32 v26, 5, v1
	v_add_u32_e32 v20, s8, v26
	v_ashrrev_i32_e32 v21, 31, v20
	v_mul_lo_u32 v1, s14, v21
	v_mul_lo_u32 v18, s15, v20
	v_mad_u64_u32 v[16:17], s[0:1], s14, v20, 0
	v_add3_u32 v17, v17, v1, v18
	v_lshl_add_u64 v[16:17], v[16:17], 2, s[12:13]
	v_ashrrev_i32_e32 v1, 31, v0
	v_lshl_add_u64 v[0:1], v[0:1], 2, v[16:17]
	v_lshl_add_u64 v[0:1], v[0:1], 0, v[2:3]
	global_load_dwordx4 v[16:19], v[0:1], off
	s_and_b64 vcc, exec, s[4:5]
	s_cbranch_vccnz .LBB0_437
	v_lshl_add_u64 v[0:1], v[20:21], 2, s[10:11]
	global_load_dword v248, v[0:1], off
	s_mov_b32 s86, 1

.LBB0_449:
	v_add_u32_e32 v8, s43, v23
	v_ashrrev_i32_e32 v9, 31, v8
	v_mul_lo_u32 v5, s28, v9
	v_mul_lo_u32 v10, s29, v8
	v_mad_u64_u32 v[6:7], s[4:5], s28, v8, 0
	v_add3_u32 v7, v7, v5, v10
	v_lshl_add_u64 v[6:7], v[6:7], 2, s[30:31]
	v_ashrrev_i32_e32 v5, 31, v4
	v_lshl_add_u64 v[4:5], v[4:5], 2, v[6:7]
	v_lshl_add_u64 v[4:5], v[4:5], 0, v[2:3]
	s_mov_b32 s86, 0
	global_load_dwordx4 v[4:7], v[4:5], off
	s_cmp_lg_u64 s[26:27], 0
	s_cselect_b64 s[34:35], -1, 0
	s_cmp_eq_u64 s[26:27], 0
	s_cbranch_scc1 .LBB0_451
	v_lshl_add_u64 v[8:9], v[8:9], 2, s[26:27]
	global_load_dword v242, v[8:9], off

.LBB0_461:
	v_add_u32_e32 v20, s43, v26
	v_ashrrev_i32_e32 v21, 31, v20
	v_mul_lo_u32 v1, s28, v21
	v_mul_lo_u32 v17, s29, v20
	v_mad_u64_u32 v[18:19], s[0:1], s28, v20, 0
	v_add3_u32 v19, v19, v1, v17
	v_lshl_add_u64 v[18:19], v[18:19], 2, s[30:31]
	v_ashrrev_i32_e32 v17, 31, v16
	v_lshl_add_u64 v[16:17], v[16:17], 2, v[18:19]
	v_lshl_add_u64 v[16:17], v[16:17], 0, v[2:3]
	global_load_dwordx4 v[16:19], v[16:17], off
	s_and_b64 vcc, exec, s[4:5]
	s_cbranch_vccnz .LBB0_438
	v_lshl_add_u64 v[20:21], v[20:21], 2, s[26:27]
	global_load_dword v248, v[20:21], off
	s_mov_b32 s86, 1
	s_branch .LBB0_438

.LBB0_758:
	v_add_u32_e32 v8, s41, v23
	v_ashrrev_i32_e32 v9, 31, v8
	v_mul_lo_u32 v5, s26, v9
	v_mul_lo_u32 v10, s27, v8
	v_mad_u64_u32 v[6:7], s[4:5], s26, v8, 0
	v_add3_u32 v7, v7, v5, v10
	v_lshl_add_u64 v[6:7], v[6:7], 2, s[28:29]
	v_ashrrev_i32_e32 v5, 31, v4
	v_lshl_add_u64 v[4:5], v[4:5], 2, v[6:7]
	v_lshl_add_u64 v[4:5], v[4:5], 0, v[2:3]
	s_mov_b32 s86, 0
	global_load_dwordx4 v[4:7], v[4:5], off
	s_cmp_lg_u64 s[24:25], 0
	s_cselect_b64 s[30:31], -1, 0
	s_cmp_eq_u64 s[24:25], 0
	s_cbranch_scc1 .LBB0_760
	v_lshl_add_u64 v[8:9], v[8:9], 2, s[24:25]
	global_load_dword v242, v[8:9], off

.LBB0_770:
	v_add_u32_e32 v20, s41, v26
	v_ashrrev_i32_e32 v21, 31, v20
	v_mul_lo_u32 v1, s26, v21
	v_mul_lo_u32 v17, s27, v20
	v_mad_u64_u32 v[18:19], s[0:1], s26, v20, 0
	v_add3_u32 v19, v19, v1, v17
	v_lshl_add_u64 v[18:19], v[18:19], 2, s[28:29]
	v_ashrrev_i32_e32 v17, 31, v16
	v_lshl_add_u64 v[16:17], v[16:17], 2, v[18:19]
	v_lshl_add_u64 v[16:17], v[16:17], 0, v[2:3]
	global_load_dwordx4 v[16:19], v[16:17], off
	s_and_b64 vcc, exec, s[4:5]
	s_cbranch_vccnz .LBB0_747
	v_lshl_add_u64 v[20:21], v[20:21], 2, s[24:25]
	global_load_dword v248, v[20:21], off
	s_mov_b32 s86, 1
	s_branch .LBB0_747

.LBB0_781:
	s_bfe_i32 s13, s7, 0x10007
	s_ashr_i32 s14, s7, 1
	s_and_b32 s13, s13, 0xb00
	s_and_b32 s14, s14, 0xffffff80
	s_add_i32 s13, s13, s14
	v_lshlrev_b32_e32 v27, 2, v28
	v_ashrrev_i32_e32 v23, 5, v28
	s_and_b64 s[0:1], s[0:1], exec
	v_and_b32_e32 v22, 64, v27
	s_cselect_b32 s0, s13, s7
	s_waitcnt vmcnt(2)
	v_add_u32_e32 v8, s6, v23
	v_or_b32_e32 v0, s0, v22
	v_mad_i64_i32 v[4:5], s[0:1], s12, v8, 0
	v_and_b32_e32 v2, 60, v27
	v_lshl_add_u64 v[4:5], v[4:5], 2, s[8:9]
	v_ashrrev_i32_e32 v1, 31, v0
	v_lshl_add_u64 v[4:5], v[0:1], 2, v[4:5]
	v_lshlrev_b32_e32 v2, 2, v2
	v_lshl_add_u64 v[4:5], v[4:5], 0, v[2:3]
	s_mov_b32 s86, 0
	global_load_dwordx4 v[4:7], v[4:5], off
	s_cmp_lg_u64 s[10:11], 0
	s_cselect_b64 s[14:15], -1, 0
	s_cmp_eq_u64 s[10:11], 0
	s_cbranch_scc1 .LBB0_783
	v_ashrrev_i32_e32 v9, 31, v8
	v_lshl_add_u64 v[8:9], v[8:9], 2, s[10:11]
	global_load_dword v242, v[8:9], off

.LBB0_787:
	v_add_u32_e32 v16, 0x600, v28
	v_ashrrev_i32_e32 v26, 5, v16
	v_add_u32_e32 v20, s6, v26
	v_mad_i64_i32 v[16:17], s[12:13], s12, v20, 0
	v_lshl_add_u64 v[16:17], v[16:17], 2, s[8:9]
	v_lshl_add_u64 v[0:1], v[0:1], 2, v[16:17]
	v_lshl_add_u64 v[0:1], v[0:1], 0, v[2:3]
	global_load_dwordx4 v[16:19], v[0:1], off
	s_and_b64 vcc, exec, s[0:1]
	s_cbranch_vccnz .LBB0_789
	v_ashrrev_i32_e32 v21, 31, v20
	v_lshl_add_u64 v[0:1], v[20:21], 2, s[10:11]
	global_load_dword v248, v[0:1], off
	s_mov_b32 s86, 1

.LBB0_797:
	s_bfe_i32 s27, s38, 0x10007
	s_ashr_i32 s28, s38, 1
	s_and_b32 s27, s27, 0xb00
	s_and_b32 s28, s28, 0xffffff80
	s_add_i32 s27, s27, s28
	s_and_b64 s[0:1], s[0:1], exec
	s_cselect_b32 s0, s27, s38
	v_add_u32_e32 v8, s40, v23
	v_or_b32_e32 v16, s0, v22
	v_mad_i64_i32 v[4:5], s[0:1], s26, v8, 0
	v_lshl_add_u64 v[4:5], v[4:5], 2, s[24:25]
	v_ashrrev_i32_e32 v17, 31, v16
	v_lshl_add_u64 v[4:5], v[16:17], 2, v[4:5]
	v_lshl_add_u64 v[4:5], v[4:5], 0, v[2:3]
	s_mov_b32 s86, 0
	global_load_dwordx4 v[4:7], v[4:5], off
	s_cmp_lg_u64 s[22:23], 0
	s_cselect_b64 s[28:29], -1, 0
	s_cmp_eq_u64 s[22:23], 0
	s_cbranch_scc1 .LBB0_799
	v_ashrrev_i32_e32 v9, 31, v8
	v_lshl_add_u64 v[8:9], v[8:9], 2, s[22:23]
	global_load_dword v242, v[8:9], off

.LBB0_803:
	v_add_u32_e32 v20, s40, v26
	v_mad_i64_i32 v[18:19], s[26:27], s26, v20, 0
	v_lshl_add_u64 v[18:19], v[18:19], 2, s[24:25]
	v_lshl_add_u64 v[16:17], v[16:17], 2, v[18:19]
	v_lshl_add_u64 v[16:17], v[16:17], 0, v[2:3]
	global_load_dwordx4 v[16:19], v[16:17], off
	s_and_b64 vcc, exec, s[0:1]
	s_cbranch_vccnz .LBB0_790
	v_ashrrev_i32_e32 v21, 31, v20
	v_lshl_add_u64 v[20:21], v[20:21], 2, s[22:23]
	global_load_dword v248, v[20:21], off
	s_mov_b32 s86, 1
	s_branch .LBB0_790
